# grid barrier spin loops: s_sleep removed (tighter polling)
# baseline (speedup 1.0000x reference)
; DI unsigned xb_ld(unsigned* p) { return __hip_atomic_load(p, __ATOMIC_RELAXED, __HIP_MEMORY_SCOPE_AGENT); }
; DI void xcd_barrier_complete(unsigned* bar, unsigned x, unsigned& nloc, unsigned& nx) {
;     ...
;   for (;;) {
;     sum = 0u; cnt = 0u; mine = 0u;
; #pragma unroll
;     for (unsigned j = 0; j < 16; ++j) { const unsigned c = xb_ld(&bar[XB_XCNT(j)]); sum += c; cnt += (c > 0u) ? 1u : 0u; mine = (j == x) ? c : mine; }
;     if (sum == G) break;
;     __builtin_amdgcn_s_sleep(1);
;     if ((++sp & 255u) == 0u) { if (xb_ld(&bar[XB_TMO])) break; if (sp > XB_SPIN_CAP) { atomicAdd(&bar[XB_TMO], 1u); break; } }
;   }
.LBB0_122:
	v_readlane_b32 s2, v252, 19
	v_readlane_b32 s3, v252, 20
	v_readlane_b32 s4, v252, 16
	s_waitcnt lgkmcnt(0)
	s_nop 2
	global_load_dword v0, v16, s[2:3] sc1
	v_readlane_b32 s2, v252, 21
	v_readlane_b32 s3, v252, 22
	s_nop 4
	global_load_dword v1, v16, s[2:3] sc1
	v_readlane_b32 s2, v252, 23
	v_readlane_b32 s3, v252, 24
	s_waitcnt vmcnt(0)
	v_add_u32_e32 v17, v1, v0
	s_nop 2
	global_load_dword v2, v16, s[2:3] sc1
	v_readlane_b32 s2, v252, 25
	v_readlane_b32 s3, v252, 26
	s_waitcnt vmcnt(0)
	v_add_u32_e32 v17, v17, v2
	s_nop 2
	global_load_dword v3, v16, s[2:3] sc1
	v_readlane_b32 s2, v252, 27
	v_readlane_b32 s3, v252, 28
	s_waitcnt vmcnt(0)
	v_add_u32_e32 v17, v17, v3
	s_nop 2
	global_load_dword v4, v16, s[2:3] sc1
	v_readlane_b32 s2, v252, 29
	v_readlane_b32 s3, v252, 30
	s_waitcnt vmcnt(0)
	v_add_u32_e32 v17, v17, v4
	s_nop 2
	global_load_dword v5, v16, s[2:3] sc1
	v_readlane_b32 s2, v252, 31
	v_readlane_b32 s3, v252, 32
	s_waitcnt vmcnt(0)
	v_add_u32_e32 v17, v17, v5
	s_nop 2
	global_load_dword v6, v16, s[2:3] sc1
	v_readlane_b32 s2, v252, 33
	v_readlane_b32 s3, v252, 34
	s_waitcnt vmcnt(0)
	v_add_u32_e32 v17, v17, v6
	s_nop 2
	global_load_dword v7, v16, s[2:3] sc1
	v_readlane_b32 s2, v252, 35
	v_readlane_b32 s3, v252, 36
	s_waitcnt vmcnt(0)
	v_add_u32_e32 v17, v17, v7
	s_nop 2
	global_load_dword v8, v16, s[2:3] sc1
	v_readlane_b32 s2, v252, 37
	v_readlane_b32 s3, v252, 38
	s_waitcnt vmcnt(0)
	v_add_u32_e32 v17, v17, v8
	s_nop 2
	global_load_dword v9, v16, s[2:3] sc1
	v_readlane_b32 s2, v252, 39
	v_readlane_b32 s3, v252, 40
	s_waitcnt vmcnt(0)
	v_add_u32_e32 v17, v17, v9
	s_nop 2
	global_load_dword v10, v16, s[2:3] sc1
	v_readlane_b32 s2, v252, 41
	v_readlane_b32 s3, v252, 42
	s_waitcnt vmcnt(0)
	v_add_u32_e32 v17, v17, v10
	s_nop 2
	global_load_dword v11, v16, s[2:3] sc1
	v_readlane_b32 s2, v252, 43
	v_readlane_b32 s3, v252, 44
	s_waitcnt vmcnt(0)
	v_add_u32_e32 v17, v17, v11
	s_nop 2
	global_load_dword v12, v16, s[2:3] sc1
	v_readlane_b32 s2, v252, 45
	v_readlane_b32 s3, v252, 46
	s_waitcnt vmcnt(0)
	v_add_u32_e32 v17, v17, v12
	s_nop 2
	global_load_dword v13, v16, s[2:3] sc1
	v_readlane_b32 s2, v252, 47
	v_readlane_b32 s3, v252, 48
	s_waitcnt vmcnt(0)
	v_add_u32_e32 v17, v17, v13
	s_nop 2
	global_load_dword v14, v16, s[2:3] sc1
	v_readlane_b32 s2, v252, 49
	v_readlane_b32 s3, v252, 50
	s_waitcnt vmcnt(0)
	v_add_u32_e32 v17, v17, v14
	s_nop 2
	global_load_dword v15, v16, s[2:3] sc1
	s_mov_b64 s[2:3], -1
	s_waitcnt vmcnt(0)
	v_add_u32_e32 v17, v17, v15
	v_cmp_eq_u32_e32 vcc, s4, v17
	s_mov_b64 s[4:5], -1
	s_cbranch_vccnz .LBB0_121
	s_and_b32 s2, s8, 0xff
	s_cmp_eq_u32 s2, 0
	s_mov_b64 s[2:3], -1
	s_mov_b64 s[6:7], -1
	s_cbranch_scc0 .LBB0_126
	v_readlane_b32 s2, v252, 17
	v_readlane_b32 s3, v252, 18
	s_nop 4
	global_load_dword v17, v16, s[2:3] sc1
	s_waitcnt vmcnt(0)
	v_cmp_eq_u32_e32 vcc, 0, v17
	s_cbranch_vccnz .LBB0_128
	s_mov_b64 s[6:7], 0
	s_mov_b64 s[2:3], -1

; DI unsigned char* wsp() { return (unsigned char*)inp(25); }
; __global__ void __launch_bounds__(512, 2) mega(Params p) {
;     ...
;   if (wsp() == nullptr) grid.sync();
.LBB0_137:
	global_load_dword v2, v0, s[2:3] offset:32 sc1
	s_waitcnt vmcnt(0)
	v_and_b32_e32 v2, 0xffff0000, v2
	v_cmp_ne_u32_e32 vcc, v2, v1
	s_or_b64 s[4:5], vcc, s[4:5]
	s_andn2_b64 exec, exec, s[4:5]
	s_cbranch_execnz .LBB0_137

; DI unsigned xb_ld(unsigned* p) { return __hip_atomic_load(p, __ATOMIC_RELAXED, __HIP_MEMORY_SCOPE_AGENT); }
; DI unsigned xb_add(unsigned* p, unsigned v) { return __hip_atomic_fetch_add(p, v, __ATOMIC_RELAXED, __HIP_MEMORY_SCOPE_AGENT); }
; #define XB_SPIN(cond, bar) do { unsigned _sp = 0; while (cond) { __builtin_amdgcn_s_sleep(1); \
;     if ((++_sp & 255u) == 0u) { if (xb_ld(&(bar)[XB_TMO])) break; if (_sp > XB_SPIN_CAP) { atomicAdd(&(bar)[XB_TMO], 1u); break; } } } } while (0)
; DI void xcd_barrier(const XcdBarrier& b) {
;     ...
;       else XB_SPIN(xb_ld(&bar[XB_TOPGEN]) == tg, bar);
;       __builtin_amdgcn_fence(__ATOMIC_ACQUIRE, "agent");
;       xb_add(&bar[XB_XGEN(b.x)], 1u);
;       asm volatile("s_waitcnt vmcnt(0)" ::: "memory");
;     } else {
;       XB_SPIN(xb_ld(&bar[XB_XGEN(b.x)]) == gen, bar);
.LBB0_151:
	s_and_b32 s12, s16, 0xff
	s_mov_b64 s[10:11], -1
	s_cmp_lg_u32 s12, 0
	s_mov_b64 s[14:15], -1
	s_cbranch_scc1 .LBB0_154
	v_readlane_b32 s12, v252, 17
	v_readlane_b32 s13, v252, 18
	s_nop 4
	global_load_dword v2, v0, s[12:13] sc1
	s_waitcnt vmcnt(0)
	v_cmp_eq_u32_e32 vcc, 0, v2
	s_cbranch_vccnz .LBB0_156
	s_mov_b64 s[14:15], 0
	s_mov_b64 s[12:13], -1

; DI unsigned xb_ld(unsigned* p) { return __hip_atomic_load(p, __ATOMIC_RELAXED, __HIP_MEMORY_SCOPE_AGENT); }
; DI unsigned xb_add(unsigned* p, unsigned v) { return __hip_atomic_fetch_add(p, v, __ATOMIC_RELAXED, __HIP_MEMORY_SCOPE_AGENT); }
; #define XB_SPIN(cond, bar) do { unsigned _sp = 0; while (cond) { __builtin_amdgcn_s_sleep(1); \
;     if ((++_sp & 255u) == 0u) { if (xb_ld(&(bar)[XB_TMO])) break; if (_sp > XB_SPIN_CAP) { atomicAdd(&(bar)[XB_TMO], 1u); break; } } } } while (0)
; DI void xcd_barrier(const XcdBarrier& b) {
;     ...
;       else XB_SPIN(xb_ld(&bar[XB_TOPGEN]) == tg, bar);
;       __builtin_amdgcn_fence(__ATOMIC_ACQUIRE, "agent");
;       xb_add(&bar[XB_XGEN(b.x)], 1u);
;       asm volatile("s_waitcnt vmcnt(0)" ::: "memory");
;     } else {
;       XB_SPIN(xb_ld(&bar[XB_XGEN(b.x)]) == gen, bar);
.LBB0_168:
	s_and_b32 s10, s16, 0xff
	s_cmp_lg_u32 s10, 0
	s_mov_b64 s[12:13], -1
	s_cbranch_scc1 .LBB0_171
	v_readlane_b32 s10, v252, 17
	v_readlane_b32 s11, v252, 18
	s_nop 4
	global_load_dword v1, v0, s[10:11] sc1
	s_waitcnt vmcnt(0)
	v_cmp_eq_u32_e32 vcc, 0, v1
	s_cbranch_vccnz .LBB0_173
	s_mov_b64 s[12:13], 0
	s_mov_b64 s[10:11], -1

; DI unsigned xb_ld(unsigned* p) { return __hip_atomic_load(p, __ATOMIC_RELAXED, __HIP_MEMORY_SCOPE_AGENT); }
; DI void xcd_barrier_complete(unsigned* bar, unsigned x, unsigned& nloc, unsigned& nx) {
;     ...
;   for (;;) {
;     sum = 0u; cnt = 0u; mine = 0u;
; #pragma unroll
;     for (unsigned j = 0; j < 16; ++j) { const unsigned c = xb_ld(&bar[XB_XCNT(j)]); sum += c; cnt += (c > 0u) ? 1u : 0u; mine = (j == x) ? c : mine; }
;     if (sum == G) break;
;     __builtin_amdgcn_s_sleep(1);
;     if ((++sp & 255u) == 0u) { if (xb_ld(&bar[XB_TMO])) break; if (sp > XB_SPIN_CAP) { atomicAdd(&bar[XB_TMO], 1u); break; } }
;   }
.LBB0_494:
	v_readlane_b32 s2, v252, 19
	v_readlane_b32 s3, v252, 20
	v_readlane_b32 s4, v252, 16
	s_waitcnt lgkmcnt(0)
	s_nop 2
	global_load_dword v0, v2, s[2:3] sc1
	v_readlane_b32 s2, v252, 21
	v_readlane_b32 s3, v252, 22
	s_nop 4
	global_load_dword v1, v2, s[2:3] sc1
	v_readlane_b32 s2, v252, 23
	v_readlane_b32 s3, v252, 24
	s_waitcnt vmcnt(0)
	v_add_u32_e32 v17, v1, v0
	s_nop 2
	global_load_dword v3, v2, s[2:3] sc1
	v_readlane_b32 s2, v252, 25
	v_readlane_b32 s3, v252, 26
	s_waitcnt vmcnt(0)
	v_add_u32_e32 v17, v17, v3
	s_nop 2
	global_load_dword v4, v2, s[2:3] sc1
	v_readlane_b32 s2, v252, 27
	v_readlane_b32 s3, v252, 28
	s_waitcnt vmcnt(0)
	v_add_u32_e32 v17, v17, v4
	s_nop 2
	global_load_dword v5, v2, s[2:3] sc1
	v_readlane_b32 s2, v252, 29
	v_readlane_b32 s3, v252, 30
	s_waitcnt vmcnt(0)
	v_add_u32_e32 v17, v17, v5
	s_nop 2
	global_load_dword v6, v2, s[2:3] sc1
	v_readlane_b32 s2, v252, 31
	v_readlane_b32 s3, v252, 32
	s_waitcnt vmcnt(0)
	v_add_u32_e32 v17, v17, v6
	s_nop 2
	global_load_dword v7, v2, s[2:3] sc1
	v_readlane_b32 s2, v252, 33
	v_readlane_b32 s3, v252, 34
	s_waitcnt vmcnt(0)
	v_add_u32_e32 v17, v17, v7
	s_nop 2
	global_load_dword v8, v2, s[2:3] sc1
	v_readlane_b32 s2, v252, 35
	v_readlane_b32 s3, v252, 36
	s_waitcnt vmcnt(0)
	v_add_u32_e32 v17, v17, v8
	s_nop 2
	global_load_dword v9, v2, s[2:3] sc1
	v_readlane_b32 s2, v252, 37
	v_readlane_b32 s3, v252, 38
	s_waitcnt vmcnt(0)
	v_add_u32_e32 v17, v17, v9
	s_nop 2
	global_load_dword v10, v2, s[2:3] sc1
	v_readlane_b32 s2, v252, 39
	v_readlane_b32 s3, v252, 40
	s_waitcnt vmcnt(0)
	v_add_u32_e32 v17, v17, v10
	s_nop 2
	global_load_dword v11, v2, s[2:3] sc1
	v_readlane_b32 s2, v252, 41
	v_readlane_b32 s3, v252, 42
	s_waitcnt vmcnt(0)
	v_add_u32_e32 v17, v17, v11
	s_nop 2
	global_load_dword v12, v2, s[2:3] sc1
	v_readlane_b32 s2, v252, 43
	v_readlane_b32 s3, v252, 44
	s_waitcnt vmcnt(0)
	v_add_u32_e32 v17, v17, v12
	s_nop 2
	global_load_dword v13, v2, s[2:3] sc1
	v_readlane_b32 s2, v252, 45
	v_readlane_b32 s3, v252, 46
	s_waitcnt vmcnt(0)
	v_add_u32_e32 v17, v17, v13
	s_nop 2
	global_load_dword v14, v2, s[2:3] sc1
	v_readlane_b32 s2, v252, 47
	v_readlane_b32 s3, v252, 48
	s_waitcnt vmcnt(0)
	v_add_u32_e32 v17, v17, v14
	s_nop 2
	global_load_dword v15, v2, s[2:3] sc1
	v_readlane_b32 s2, v252, 49
	v_readlane_b32 s3, v252, 50
	s_waitcnt vmcnt(0)
	v_add_u32_e32 v17, v17, v15
	s_nop 2
	global_load_dword v16, v2, s[2:3] sc1
	s_mov_b64 s[2:3], -1
	s_waitcnt vmcnt(0)
	v_add_u32_e32 v17, v17, v16
	v_cmp_eq_u32_e32 vcc, s4, v17
	s_mov_b64 s[4:5], -1
	s_cbranch_vccnz .LBB0_493
	s_and_b32 s2, s7, 0xff
	s_cmp_eq_u32 s2, 0
	s_mov_b64 s[2:3], -1
	s_mov_b64 s[12:13], -1
	s_cbranch_scc0 .LBB0_498
	v_readlane_b32 s2, v252, 17
	v_readlane_b32 s3, v252, 18
	s_nop 4
	global_load_dword v17, v2, s[2:3] sc1
	s_waitcnt vmcnt(0)
	v_cmp_eq_u32_e32 vcc, 0, v17
	s_cbranch_vccnz .LBB0_500
	s_mov_b64 s[12:13], 0
	s_mov_b64 s[2:3], -1

; DI unsigned xb_ld(unsigned* p) { return __hip_atomic_load(p, __ATOMIC_RELAXED, __HIP_MEMORY_SCOPE_AGENT); }
; #define XB_SPIN(cond, bar) do { unsigned _sp = 0; while (cond) { __builtin_amdgcn_s_sleep(1); \
;     if ((++_sp & 255u) == 0u) { if (xb_ld(&(bar)[XB_TMO])) break; if (_sp > XB_SPIN_CAP) { atomicAdd(&(bar)[XB_TMO], 1u); break; } } } } while (0)
; DI void xcd_barrier(const XcdBarrier& b) {
;     ...
;       XB_SPIN(xb_ld(&bar[XB_XGEN(b.x)]) == gen, bar);
.LBB0_512:
	s_and_b32 s24, s7, 0xff
	s_mov_b64 s[20:21], -1
	s_cmp_lg_u32 s24, 0
	s_mov_b64 s[30:31], -1
	s_cbranch_scc1 .LBB0_515
	v_readlane_b32 s24, v252, 17
	v_readlane_b32 s25, v252, 18
	s_nop 4
	global_load_dword v0, v2, s[24:25] sc1
	s_waitcnt vmcnt(0)
	v_cmp_eq_u32_e32 vcc, 0, v0
	s_cbranch_vccnz .LBB0_517
	s_mov_b64 s[30:31], 0
	s_mov_b64 s[24:25], -1

; DI unsigned xb_ld(unsigned* p) { return __hip_atomic_load(p, __ATOMIC_RELAXED, __HIP_MEMORY_SCOPE_AGENT); }
; DI void xcd_barrier_complete(unsigned* bar, unsigned x, unsigned& nloc, unsigned& nx) {
;     ...
;   for (;;) {
;     sum = 0u; cnt = 0u; mine = 0u;
; #pragma unroll
;     for (unsigned j = 0; j < 16; ++j) { const unsigned c = xb_ld(&bar[XB_XCNT(j)]); sum += c; cnt += (c > 0u) ? 1u : 0u; mine = (j == x) ? c : mine; }
;     if (sum == G) break;
;     __builtin_amdgcn_s_sleep(1);
;     if ((++sp & 255u) == 0u) { if (xb_ld(&bar[XB_TMO])) break; if (sp > XB_SPIN_CAP) { atomicAdd(&bar[XB_TMO], 1u); break; } }
;   }
.LBB0_582:
	v_readlane_b32 s2, v252, 19
	v_readlane_b32 s3, v252, 20
	v_readlane_b32 s4, v252, 16
	s_waitcnt lgkmcnt(0)
	s_nop 2
	global_load_dword v0, v2, s[2:3] sc1
	v_readlane_b32 s2, v252, 21
	v_readlane_b32 s3, v252, 22
	s_nop 4
	global_load_dword v1, v2, s[2:3] sc1
	v_readlane_b32 s2, v252, 23
	v_readlane_b32 s3, v252, 24
	s_waitcnt vmcnt(0)
	v_add_u32_e32 v17, v1, v0
	s_nop 2
	global_load_dword v3, v2, s[2:3] sc1
	v_readlane_b32 s2, v252, 25
	v_readlane_b32 s3, v252, 26
	s_waitcnt vmcnt(0)
	v_add_u32_e32 v17, v17, v3
	s_nop 2
	global_load_dword v4, v2, s[2:3] sc1
	v_readlane_b32 s2, v252, 27
	v_readlane_b32 s3, v252, 28
	s_waitcnt vmcnt(0)
	v_add_u32_e32 v17, v17, v4
	s_nop 2
	global_load_dword v5, v2, s[2:3] sc1
	v_readlane_b32 s2, v252, 29
	v_readlane_b32 s3, v252, 30
	s_waitcnt vmcnt(0)
	v_add_u32_e32 v17, v17, v5
	s_nop 2
	global_load_dword v6, v2, s[2:3] sc1
	v_readlane_b32 s2, v252, 31
	v_readlane_b32 s3, v252, 32
	s_waitcnt vmcnt(0)
	v_add_u32_e32 v17, v17, v6
	s_nop 2
	global_load_dword v7, v2, s[2:3] sc1
	v_readlane_b32 s2, v252, 33
	v_readlane_b32 s3, v252, 34
	s_waitcnt vmcnt(0)
	v_add_u32_e32 v17, v17, v7
	s_nop 2
	global_load_dword v8, v2, s[2:3] sc1
	v_readlane_b32 s2, v252, 35
	v_readlane_b32 s3, v252, 36
	s_waitcnt vmcnt(0)
	v_add_u32_e32 v17, v17, v8
	s_nop 2
	global_load_dword v9, v2, s[2:3] sc1
	v_readlane_b32 s2, v252, 37
	v_readlane_b32 s3, v252, 38
	s_waitcnt vmcnt(0)
	v_add_u32_e32 v17, v17, v9
	s_nop 2
	global_load_dword v10, v2, s[2:3] sc1
	v_readlane_b32 s2, v252, 39
	v_readlane_b32 s3, v252, 40
	s_waitcnt vmcnt(0)
	v_add_u32_e32 v17, v17, v10
	s_nop 2
	global_load_dword v11, v2, s[2:3] sc1
	v_readlane_b32 s2, v252, 41
	v_readlane_b32 s3, v252, 42
	s_waitcnt vmcnt(0)
	v_add_u32_e32 v17, v17, v11
	s_nop 2
	global_load_dword v12, v2, s[2:3] sc1
	v_readlane_b32 s2, v252, 43
	v_readlane_b32 s3, v252, 44
	s_waitcnt vmcnt(0)
	v_add_u32_e32 v17, v17, v12
	s_nop 2
	global_load_dword v13, v2, s[2:3] sc1
	v_readlane_b32 s2, v252, 45
	v_readlane_b32 s3, v252, 46
	s_waitcnt vmcnt(0)
	v_add_u32_e32 v17, v17, v13
	s_nop 2
	global_load_dword v14, v2, s[2:3] sc1
	v_readlane_b32 s2, v252, 47
	v_readlane_b32 s3, v252, 48
	s_waitcnt vmcnt(0)
	v_add_u32_e32 v17, v17, v14
	s_nop 2
	global_load_dword v15, v2, s[2:3] sc1
	v_readlane_b32 s2, v252, 49
	v_readlane_b32 s3, v252, 50
	s_waitcnt vmcnt(0)
	v_add_u32_e32 v17, v17, v15
	s_nop 2
	global_load_dword v16, v2, s[2:3] sc1
	s_mov_b64 s[2:3], -1
	s_waitcnt vmcnt(0)
	v_add_u32_e32 v17, v17, v16
	v_cmp_eq_u32_e32 vcc, s4, v17
	s_mov_b64 s[4:5], -1
	s_cbranch_vccnz .LBB0_581
	s_and_b32 s2, s7, 0xff
	s_cmp_eq_u32 s2, 0
	s_mov_b64 s[2:3], -1
	s_mov_b64 s[8:9], -1
	s_cbranch_scc0 .LBB0_586
	v_readlane_b32 s2, v252, 17
	v_readlane_b32 s3, v252, 18
	s_nop 4
	global_load_dword v17, v2, s[2:3] sc1
	s_waitcnt vmcnt(0)
	v_cmp_eq_u32_e32 vcc, 0, v17
	s_cbranch_vccnz .LBB0_588
	s_mov_b64 s[8:9], 0
	s_mov_b64 s[2:3], -1

; DI unsigned xb_ld(unsigned* p) { return __hip_atomic_load(p, __ATOMIC_RELAXED, __HIP_MEMORY_SCOPE_AGENT); }
; #define XB_SPIN(cond, bar) do { unsigned _sp = 0; while (cond) { __builtin_amdgcn_s_sleep(1); \
;     if ((++_sp & 255u) == 0u) { if (xb_ld(&(bar)[XB_TMO])) break; if (_sp > XB_SPIN_CAP) { atomicAdd(&(bar)[XB_TMO], 1u); break; } } } } while (0)
; DI void xcd_barrier(const XcdBarrier& b) {
;     ...
;       XB_SPIN(xb_ld(&bar[XB_XGEN(b.x)]) == gen, bar);
.LBB0_600:
	s_and_b32 s20, s7, 0xff
	s_mov_b64 s[14:15], -1
	s_cmp_lg_u32 s20, 0
	s_mov_b64 s[24:25], -1
	s_cbranch_scc1 .LBB0_603
	v_readlane_b32 s20, v252, 17
	v_readlane_b32 s21, v252, 18
	s_nop 4
	global_load_dword v0, v2, s[20:21] sc1
	s_waitcnt vmcnt(0)
	v_cmp_eq_u32_e32 vcc, 0, v0
	s_cbranch_vccnz .LBB0_605
	s_mov_b64 s[24:25], 0
	s_mov_b64 s[20:21], -1

; DI unsigned xb_ld(unsigned* p) { return __hip_atomic_load(p, __ATOMIC_RELAXED, __HIP_MEMORY_SCOPE_AGENT); }
; DI void xcd_barrier_complete(unsigned* bar, unsigned x, unsigned& nloc, unsigned& nx) {
;     ...
;   for (;;) {
;     sum = 0u; cnt = 0u; mine = 0u;
; #pragma unroll
;     for (unsigned j = 0; j < 16; ++j) { const unsigned c = xb_ld(&bar[XB_XCNT(j)]); sum += c; cnt += (c > 0u) ? 1u : 0u; mine = (j == x) ? c : mine; }
;     if (sum == G) break;
;     __builtin_amdgcn_s_sleep(1);
;     if ((++sp & 255u) == 0u) { if (xb_ld(&bar[XB_TMO])) break; if (sp > XB_SPIN_CAP) { atomicAdd(&bar[XB_TMO], 1u); break; } }
;   }
.LBB0_854:
	v_readlane_b32 s2, v252, 19
	v_readlane_b32 s3, v252, 20
	v_readlane_b32 s4, v252, 16
	s_waitcnt lgkmcnt(0)
	s_nop 2
	global_load_dword v0, v2, s[2:3] sc1
	v_readlane_b32 s2, v252, 21
	v_readlane_b32 s3, v252, 22
	s_nop 4
	global_load_dword v1, v2, s[2:3] sc1
	v_readlane_b32 s2, v252, 23
	v_readlane_b32 s3, v252, 24
	s_waitcnt vmcnt(0)
	v_add_u32_e32 v17, v1, v0
	s_nop 2
	global_load_dword v3, v2, s[2:3] sc1
	v_readlane_b32 s2, v252, 25
	v_readlane_b32 s3, v252, 26
	s_waitcnt vmcnt(0)
	v_add_u32_e32 v17, v17, v3
	s_nop 2
	global_load_dword v4, v2, s[2:3] sc1
	v_readlane_b32 s2, v252, 27
	v_readlane_b32 s3, v252, 28
	s_waitcnt vmcnt(0)
	v_add_u32_e32 v17, v17, v4
	s_nop 2
	global_load_dword v5, v2, s[2:3] sc1
	v_readlane_b32 s2, v252, 29
	v_readlane_b32 s3, v252, 30
	s_waitcnt vmcnt(0)
	v_add_u32_e32 v17, v17, v5
	s_nop 2
	global_load_dword v6, v2, s[2:3] sc1
	v_readlane_b32 s2, v252, 31
	v_readlane_b32 s3, v252, 32
	s_waitcnt vmcnt(0)
	v_add_u32_e32 v17, v17, v6
	s_nop 2
	global_load_dword v7, v2, s[2:3] sc1
	v_readlane_b32 s2, v252, 33
	v_readlane_b32 s3, v252, 34
	s_waitcnt vmcnt(0)
	v_add_u32_e32 v17, v17, v7
	s_nop 2
	global_load_dword v8, v2, s[2:3] sc1
	v_readlane_b32 s2, v252, 35
	v_readlane_b32 s3, v252, 36
	s_waitcnt vmcnt(0)
	v_add_u32_e32 v17, v17, v8
	s_nop 2
	global_load_dword v9, v2, s[2:3] sc1
	v_readlane_b32 s2, v252, 37
	v_readlane_b32 s3, v252, 38
	s_waitcnt vmcnt(0)
	v_add_u32_e32 v17, v17, v9
	s_nop 2
	global_load_dword v10, v2, s[2:3] sc1
	v_readlane_b32 s2, v252, 39
	v_readlane_b32 s3, v252, 40
	s_waitcnt vmcnt(0)
	v_add_u32_e32 v17, v17, v10
	s_nop 2
	global_load_dword v11, v2, s[2:3] sc1
	v_readlane_b32 s2, v252, 41
	v_readlane_b32 s3, v252, 42
	s_waitcnt vmcnt(0)
	v_add_u32_e32 v17, v17, v11
	s_nop 2
	global_load_dword v12, v2, s[2:3] sc1
	v_readlane_b32 s2, v252, 43
	v_readlane_b32 s3, v252, 44
	s_waitcnt vmcnt(0)
	v_add_u32_e32 v17, v17, v12
	s_nop 2
	global_load_dword v13, v2, s[2:3] sc1
	v_readlane_b32 s2, v252, 45
	v_readlane_b32 s3, v252, 46
	s_waitcnt vmcnt(0)
	v_add_u32_e32 v17, v17, v13
	s_nop 2
	global_load_dword v14, v2, s[2:3] sc1
	v_readlane_b32 s2, v252, 47
	v_readlane_b32 s3, v252, 48
	s_waitcnt vmcnt(0)
	v_add_u32_e32 v17, v17, v14
	s_nop 2
	global_load_dword v15, v2, s[2:3] sc1
	v_readlane_b32 s2, v252, 49
	v_readlane_b32 s3, v252, 50
	s_waitcnt vmcnt(0)
	v_add_u32_e32 v17, v17, v15
	s_nop 2
	global_load_dword v16, v2, s[2:3] sc1
	s_mov_b64 s[2:3], -1
	s_waitcnt vmcnt(0)
	v_add_u32_e32 v17, v17, v16
	v_cmp_eq_u32_e32 vcc, s4, v17
	s_mov_b64 s[4:5], -1
	s_cbranch_vccnz .LBB0_853
	s_and_b32 s2, s8, 0xff
	s_cmp_eq_u32 s2, 0
	s_mov_b64 s[2:3], -1
	s_mov_b64 s[6:7], -1
	s_cbranch_scc0 .LBB0_858
	v_readlane_b32 s2, v252, 17
	v_readlane_b32 s3, v252, 18
	s_nop 4
	global_load_dword v17, v2, s[2:3] sc1
	s_waitcnt vmcnt(0)
	v_cmp_eq_u32_e32 vcc, 0, v17
	s_cbranch_vccnz .LBB0_860
	s_mov_b64 s[6:7], 0
	s_mov_b64 s[2:3], -1

; DI unsigned xb_ld(unsigned* p) { return __hip_atomic_load(p, __ATOMIC_RELAXED, __HIP_MEMORY_SCOPE_AGENT); }
; #define XB_SPIN(cond, bar) do { unsigned _sp = 0; while (cond) { __builtin_amdgcn_s_sleep(1); \
;     if ((++_sp & 255u) == 0u) { if (xb_ld(&(bar)[XB_TMO])) break; if (_sp > XB_SPIN_CAP) { atomicAdd(&(bar)[XB_TMO], 1u); break; } } } } while (0)
; DI void xcd_barrier(const XcdBarrier& b) {
;     ...
;       XB_SPIN(xb_ld(&bar[XB_XGEN(b.x)]) == gen, bar);
.LBB0_872:
	s_and_b32 s14, s24, 0xff
	s_mov_b64 s[12:13], -1
	s_cmp_lg_u32 s14, 0
	s_mov_b64 s[20:21], -1
	s_cbranch_scc1 .LBB0_875
	v_readlane_b32 s14, v252, 17
	v_readlane_b32 s15, v252, 18
	s_nop 4
	global_load_dword v0, v2, s[14:15] sc1
	s_waitcnt vmcnt(0)
	v_cmp_eq_u32_e32 vcc, 0, v0
	s_cbranch_vccnz .LBB0_877
	s_mov_b64 s[20:21], 0
	s_mov_b64 s[14:15], -1
